# NA half-specialised loops: the PV k-step whose 16 keys are outside every lane's column window is dropped (2 MFMAs, 2 V fragment reads, 4 cvt per tile per wave); probabilities there are exactly zero
# baseline (speedup 1.0000x reference)
; #define LAS __attribute__((address_space(3)))
; #define SBAR_() __builtin_amdgcn_sched_barrier(0)
; template <int MODE, bool FROZEN = false>
; __device__ __forceinline__ bool attn_unit(LAS unsigned char* lds, const Params& p, int l, int ua, int ub) {
;     ...
;             const size_t advk = (size_t)min(t + 3, NT - 1) * 64 * NPROJ, advv = (size_t)min(t + 2, NT - 1) * 64;
; #pragma unroll
;             for (int i = 0; i < NKC; ++i) kr[i] = *(const u32x4*)(kvbase + advk + ksrc[i]);
; #pragma unroll
;             for (int i = 0; i < NVC; ++i) vr[i] = *(const u32x4*)(vtbase + advv + vsrc[i]);
;         }
;         f32x16 sA0 = sB0, sA1 = sB1;
;         const float c2 = cbB - m_run;
;         const LAS unsigned char* Vb = lds + OFF_V + (t & 1) * VBUF + vlane_off;
;         const LAS unsigned char* Kb = lds + OFF_K + ((t + 1) & 1) * KBUF + klane_off;
;     ...
;         bf16x8 kf0[4], kf1[4], va[NB], vb[NB], pf0, pf1; float ps0, ps1, ps2, ps3;
;         VLOAD(0, va);
;         EXPCVT(0, pf0, ps0);
;         SBAR_();
;         VLOAD(1, vb); PVMMA(va, pf0); EXPCVT(1, pf1, ps1); _Pragma("unroll") for (int g_ = 0; g_ < NB; ++g_) { __builtin_amdgcn_sched_group_barrier(0x008, 1, 0); __builtin_amdgcn_sched_group_barrier(0x100, 1, 0); __builtin_amdgcn_sched_group_barrier(0x400, 8 / NB, 0); __builtin_amdgcn_sched_group_barrier(0x002, 12 / NB, 0); } SBAR_();
;         VLOAD(2, va);
; #pragma unroll
;         for (int d0 = 0; d0 < 4; ++d0) { kf0[d0] = *(const LAS bf16x8*)(Kb + d0 * 32); kf1[d0] = *(const LAS bf16x8*)(Kb + 32 * KPB + d0 * 32); }
;         PVMMA(vb, pf1); EXPCVT(2, pf0, ps2); _Pragma("unroll") for (int g_ = 0; g_ < NB; ++g_) { __builtin_amdgcn_sched_group_barrier(0x008, 1, 0); __builtin_amdgcn_sched_group_barrier(0x100, 1, 0); __builtin_amdgcn_sched_group_barrier(0x400, 8 / NB, 0); __builtin_amdgcn_sched_group_barrier(0x002, 12 / NB, 0); } SBAR_();
;         {
;             f32x16 z0, z1;
; #pragma unroll
;             for (int r = 0; r < 16; ++r) { z0[r] = 0.f; z1[r] = 0.f; }
; #pragma unroll
;             for (int d0 = 0; d0 < 4; ++d0) { z0 = __builtin_amdgcn_mfma_f32_32x32x16_bf16(kf0[d0], qf[d0], z0, 0, 0, 0); z1 = __builtin_amdgcn_mfma_f32_32x32x16_bf16(kf1[d0], qf[d0], z1, 0, 0, 0); }
;             sB0 = z0; sB1 = z1;
;         }
;         EXPCVT(3, pf1, ps3);
; #pragma unroll
.LBB0_264:
	s_add_i32 s12, s21, 3
	s_min_i32 vcc_lo, s12, s18
	s_min_i32 s12, s23, s18
	s_ashr_i32 s13, s12, 31
	s_lshl_b64 s[12:13], s[12:13], 7
	v_mad_i64_i32 v[68:69], vcc, vcc_lo, v243, v[126:127]
	v_lshl_add_u64 v[70:71], v[128:129], 0, s[12:13]
	global_load_dwordx4 v[120:123], v[68:69], off
	global_load_dwordx4 v[116:119], v[70:71], off
	s_add_i32 s100, s21, 1
	s_cmp_lt_i32 s100, s16
	s_cbranch_scc1 .LBB0_334
	s_cmp_gt_i32 s21, s8
	s_cbranch_scc1 .LBB0_334
	v_add_f32_e64 v35, -v152, v52
	v_exp_f32_e32 v84, v35
	v_add_f32_e64 v35, -v152, v53
	v_exp_f32_e32 v86, v35
	v_add_f32_e64 v35, -v152, v54
	v_exp_f32_e32 v138, v35
	v_add_f32_e64 v35, -v152, v55
	v_exp_f32_e32 v142, v35
	v_add_f32_e64 v35, -v152, v56
	v_exp_f32_e32 v134, v35
	v_add_f32_e64 v35, -v152, v57
	s_bitcmp1_b32 s21, 0
	v_exp_f32_e32 v140, v35
	v_add_f32_e64 v35, -v152, v58
	s_cselect_b32 s12, 0x2400, 0
	v_exp_f32_e32 v132, v35
	v_add_f32_e64 v35, -v152, v59
	v_add_u32_e32 v1, s12, v150
	v_exp_f32_e32 v136, v35
	ds_read_b128 v[68:71], v1 offset:18432
	ds_read_b128 v[72:75], v1 offset:23040
	v_cvt_pk_bf16_f32 v52, v84, v86
	v_cvt_pk_bf16_f32 v53, v138, v142
	v_cvt_pk_bf16_f32 v54, v134, v140
	v_cvt_pk_bf16_f32 v55, v132, v136
	s_waitcnt lgkmcnt(1)
	s_nop 0
	v_mfma_f32_32x32x16_bf16 v[2:17], v[68:71], v[52:55], v[2:17]
	ds_read_b128 v[56:59], v1 offset:18464
	v_add_f32_e64 v60, -v152, v60
	v_exp_f32_e32 v98, v60
	v_add_f32_e64 v61, -v152, v61
	v_exp_f32_e32 v96, v61
	v_add_f32_e64 v62, -v152, v62
	v_exp_f32_e32 v146, v62
	v_add_f32_e64 v35, -v152, v64
	v_exp_f32_e32 v90, v35
	v_add_f32_e64 v35, -v152, v65
	v_exp_f32_e32 v94, v35
	v_add_f32_e64 v35, -v152, v66
	v_exp_f32_e32 v88, v35
	v_add_f32_e64 v35, -v152, v67
	v_exp_f32_e32 v92, v35
	v_add_f32_e64 v35, -v152, v63
	v_exp_f32_e32 v144, v35
	v_cvt_pk_bf16_f32 v62, v90, v94
	v_cvt_pk_bf16_f32 v63, v88, v92
	v_cvt_pk_bf16_f32 v61, v146, v144
	s_waitcnt lgkmcnt(1)
	v_mfma_f32_32x32x16_bf16 v[18:33], v[72:75], v[52:55], v[18:33]
	ds_read_b128 v[52:55], v1 offset:23072
	v_cvt_pk_bf16_f32 v60, v98, v96
	v_add_u32_e32 v35, s22, v149
	s_waitcnt lgkmcnt(1)
	v_mfma_f32_32x32x16_bf16 v[2:17], v[56:59], v[60:63], v[2:17]
	ds_read_b128 v[72:75], v1 offset:18496
	v_add_f32_e64 v36, -v152, v36
	v_exp_f32_e32 v85, v36
	v_mov_b32_e32 v137, 0
	v_add_f32_e64 v37, -v152, v37
	v_exp_f32_e32 v87, v37
	v_mov_b32_e32 v133, 0
	v_add_f32_e64 v38, -v152, v38
	v_exp_f32_e32 v139, v38
	v_mov_b32_e32 v141, 0
	v_add_f32_e64 v39, -v152, v39
	v_exp_f32_e32 v143, v39
	v_mov_b32_e32 v135, 0
	v_cvt_pk_bf16_f32 v83, v133, v137
	ds_read_b128 v[36:39], v35 offset:4608
	ds_read_b128 v[56:59], v35 offset:4640
	v_cvt_pk_bf16_f32 v82, v135, v141
	s_waitcnt lgkmcnt(3)
	v_mfma_f32_32x32x16_bf16 v[18:33], v[52:55], v[60:63], v[18:33]
	ds_read_b128 v[52:55], v35
	ds_read_b128 v[60:63], v35 offset:4672
	ds_read_b128 v[64:67], v35 offset:4704
	ds_read_b128 v[68:71], v1 offset:23104
	ds_read_b128 v[154:157], v35 offset:32
	ds_read_b128 v[158:161], v35 offset:64
	ds_read_b128 v[162:165], v35 offset:96
	v_cvt_pk_bf16_f32 v80, v85, v87
	v_cvt_pk_bf16_f32 v81, v139, v143
	v_mov_b32_e32 v93, 0
	v_mov_b32_e32 v99, 0
	v_mov_b32_e32 v147, 0
	v_mov_b32_e32 v89, 0
	v_mov_b32_e32 v97, 0
	s_waitcnt lgkmcnt(8)
	v_mfma_f32_32x32x16_bf16 v[36:51], v[36:39], v[100:103], v[176:191]
	s_waitcnt lgkmcnt(7)
	v_mfma_f32_32x32x16_bf16 v[36:51], v[56:59], v[104:107], v[36:51]
	s_waitcnt lgkmcnt(5)
	v_mfma_f32_32x32x16_bf16 v[36:51], v[60:63], v[108:111], v[36:51]
	s_waitcnt lgkmcnt(4)
	v_mfma_f32_32x32x16_bf16 v[36:51], v[64:67], v[112:115], v[36:51]
	v_mfma_f32_32x32x16_bf16 v[52:67], v[52:55], v[100:103], v[202:217]
	s_waitcnt lgkmcnt(2)
	v_mfma_f32_32x32x16_bf16 v[52:67], v[154:157], v[104:107], v[52:67]
	s_waitcnt lgkmcnt(1)
	v_mfma_f32_32x32x16_bf16 v[52:67], v[158:161], v[108:111], v[52:67]
	v_mov_b32_e32 v145, 0
	v_mov_b32_e32 v91, 0
	v_mov_b32_e32 v95, 0
	s_waitcnt lgkmcnt(0)
	v_mfma_f32_32x32x16_bf16 v[52:67], v[162:165], v[112:115], v[52:67]
	v_mfma_f32_32x32x16_bf16 v[2:17], v[72:75], v[80:83], v[2:17]
	v_add_f32_e64 v72, v138, v142
	v_add_f32_e64 v73, v139, v143
	v_add_f32_e64 v74, v134, v140
	v_add_f32_e64 v75, v135, v141
	v_add_f32_e64 v132, v132, v136
	v_add_f32_e64 v133, v133, v137
	v_pk_add_f32 v[84:85], v[84:85], v[86:87]
	v_pk_add_f32 v[74:75], v[74:75], v[132:133]
	s_andn2_b64 vcc, exec, s[10:11]
	v_mfma_f32_32x32x16_bf16 v[18:33], v[68:71], v[80:83], v[18:33]
	v_add_f32_e64 v68, v84, v72
	v_add_f32_e64 v69, v85, v73
	v_add_f32_e64 v72, v90, v94
	v_add_f32_e64 v73, v91, v95
	v_add_f32_e64 v68, v68, v74
	v_add_f32_e64 v69, v69, v75
	v_pk_add_f32 v[74:75], v[88:89], v[92:93]
	v_pk_add_f32 v[70:71], v[146:147], v[144:145]
	v_pk_add_f32 v[72:73], v[72:73], v[74:75]
	v_pk_add_f32 v[74:75], v[98:99], v[96:97]
	s_waitcnt lgkmcnt(1)
	v_add_f32_e64 v70, v74, v70
	v_add_f32_e64 v71, v75, v71
	v_add_f32_e64 v70, v70, v72
	v_add_f32_e64 v71, v71, v73
	v_add_f32_e64 v68, v68, v70
	v_add_f32_e64 v69, v69, v71
	v_add_f32_e32 v1, v68, v69
	s_waitcnt lgkmcnt(0)
	v_add_f32_e32 v0, v0, v1
	s_cbranch_vccnz .LBB0_334
	s_cmp_lt_i32 s20, s16
	s_cselect_b64 s[10:11], -1, 0
	s_cmp_ge_i32 s21, s8
	s_cselect_b64 s[12:13], -1, 0
	s_or_b64 s[10:11], s[12:13], s[10:11]
	s_and_b64 vcc, exec, s[10:11]
	s_cbranch_vccnz .LBB0_331
	s_add_i32 s10, s19, s21
	s_max_i32 s10, s10, -7
	s_add_i32 s10, s10, 7
	s_min_u32 s10, s10, 14
	s_mulk_i32 s10, 0x1fc
	v_add_u32_e32 v1, s10, v151
	v_mov_b32_e32 v35, 0xf149f2ca
	ds_read_b32 v68, v1 offset:36864
	ds_read_b32 v69, v1 offset:36992
	ds_read_b32 v70, v1 offset:36868
	ds_read_b32 v71, v1 offset:36996
	ds_read_b32 v72, v1 offset:36872
	ds_read_b32 v73, v1 offset:37000
	ds_read_b32 v74, v1 offset:36876
	ds_read_b32 v75, v1 offset:37004
	ds_read_b32 v76, v1 offset:36896
	ds_read_b32 v78, v1 offset:36900
	ds_read_b32 v80, v1 offset:36904
	ds_read_b32 v82, v1 offset:36908
	ds_read_b32 v84, v1 offset:36928
	ds_read_b32 v86, v1 offset:36932
	ds_read_b32 v88, v1 offset:36936
	s_waitcnt lgkmcnt(14)
	v_add_f32_e32 v52, v52, v68
	ds_read_b32 v90, v1 offset:36940
	s_waitcnt lgkmcnt(14)
	v_add_f32_e32 v36, v36, v69
	ds_read_b32 v92, v1 offset:36960
	s_waitcnt lgkmcnt(14)
	v_add_f32_e32 v53, v53, v70
	ds_read_b32 v94, v1 offset:36964
	s_waitcnt lgkmcnt(14)
	v_add_f32_e32 v37, v37, v71
	ds_read_b32 v96, v1 offset:36968
	s_waitcnt lgkmcnt(14)
	v_add_f32_e32 v54, v54, v72
	ds_read_b32 v98, v1 offset:36972
	s_waitcnt lgkmcnt(14)
	v_add_f32_e32 v38, v38, v73
	s_waitcnt lgkmcnt(13)
	v_add_f32_e32 v55, v55, v74
	s_waitcnt lgkmcnt(12)
	v_add_f32_e32 v39, v39, v75
	s_waitcnt lgkmcnt(11)
	v_add_f32_e32 v56, v56, v76
	s_waitcnt lgkmcnt(10)
	v_add_f32_e32 v57, v57, v78
	s_waitcnt lgkmcnt(9)
	v_add_f32_e32 v58, v58, v80
	s_waitcnt lgkmcnt(8)
	v_add_f32_e32 v59, v59, v82
	s_waitcnt lgkmcnt(7)
	v_add_f32_e32 v60, v60, v84
	s_waitcnt lgkmcnt(6)
	v_add_f32_e32 v61, v61, v86
	s_waitcnt lgkmcnt(5)
	v_add_f32_e32 v62, v62, v88
	s_waitcnt lgkmcnt(4)
	v_add_f32_e32 v63, v63, v90
	s_waitcnt lgkmcnt(3)
	v_add_f32_e32 v64, v64, v92
	s_waitcnt lgkmcnt(2)
	v_add_f32_e32 v65, v65, v94
	s_waitcnt lgkmcnt(1)
	v_add_f32_e32 v66, v66, v96
	s_waitcnt lgkmcnt(0)
	v_add_f32_e32 v67, v67, v98
	s_branch .LBB0_332

; #define LAS __attribute__((address_space(3)))
; #define SBAR_() __builtin_amdgcn_sched_barrier(0)
; template <int MODE, bool FROZEN = false>
; __device__ __forceinline__ bool attn_unit(LAS unsigned char* lds, const Params& p, int l, int ua, int ub) {
;     ...
;             const size_t advk = (size_t)min(t + 3, NT - 1) * 64 * NPROJ, advv = (size_t)min(t + 2, NT - 1) * 64;
; #pragma unroll
;             for (int i = 0; i < NKC; ++i) kr[i] = *(const u32x4*)(kvbase + advk + ksrc[i]);
; #pragma unroll
;             for (int i = 0; i < NVC; ++i) vr[i] = *(const u32x4*)(vtbase + advv + vsrc[i]);
;         }
;         f32x16 sA0 = sB0, sA1 = sB1;
;         const float c2 = cbB - m_run;
;         const LAS unsigned char* Vb = lds + OFF_V + (t & 1) * VBUF + vlane_off;
;         const LAS unsigned char* Kb = lds + OFF_K + ((t + 1) & 1) * KBUF + klane_off;
;     ...
;         bf16x8 kf0[4], kf1[4], va[NB], vb[NB], pf0, pf1; float ps0, ps1, ps2, ps3;
;         VLOAD(0, va);
;         EXPCVT(0, pf0, ps0);
;         SBAR_();
;         VLOAD(1, vb); PVMMA(va, pf0); EXPCVT(1, pf1, ps1); _Pragma("unroll") for (int g_ = 0; g_ < NB; ++g_) { __builtin_amdgcn_sched_group_barrier(0x008, 1, 0); __builtin_amdgcn_sched_group_barrier(0x100, 1, 0); __builtin_amdgcn_sched_group_barrier(0x400, 8 / NB, 0); __builtin_amdgcn_sched_group_barrier(0x002, 12 / NB, 0); } SBAR_();
;         VLOAD(2, va);
; #pragma unroll
;         for (int d0 = 0; d0 < 4; ++d0) { kf0[d0] = *(const LAS bf16x8*)(Kb + d0 * 32); kf1[d0] = *(const LAS bf16x8*)(Kb + 32 * KPB + d0 * 32); }
;         PVMMA(vb, pf1); EXPCVT(2, pf0, ps2); _Pragma("unroll") for (int g_ = 0; g_ < NB; ++g_) { __builtin_amdgcn_sched_group_barrier(0x008, 1, 0); __builtin_amdgcn_sched_group_barrier(0x100, 1, 0); __builtin_amdgcn_sched_group_barrier(0x400, 8 / NB, 0); __builtin_amdgcn_sched_group_barrier(0x002, 12 / NB, 0); } SBAR_();
;         {
;             f32x16 z0, z1;
; #pragma unroll
;             for (int r = 0; r < 16; ++r) { z0[r] = 0.f; z1[r] = 0.f; }
; #pragma unroll
;             for (int d0 = 0; d0 < 4; ++d0) { z0 = __builtin_amdgcn_mfma_f32_32x32x16_bf16(kf0[d0], qf[d0], z0, 0, 0, 0); z1 = __builtin_amdgcn_mfma_f32_32x32x16_bf16(kf1[d0], qf[d0], z1, 0, 0, 0); }
;             sB0 = z0; sB1 = z1;
;         }
;         EXPCVT(3, pf1, ps3);
; #pragma unroll
.LBB0_264_h1:
	s_add_i32 s12, s21, 3
	s_min_i32 vcc_lo, s12, s18
	s_min_i32 s12, s23, s18
	s_ashr_i32 s13, s12, 31
	s_lshl_b64 s[12:13], s[12:13], 7
	v_mad_i64_i32 v[68:69], vcc, vcc_lo, v243, v[126:127]
	v_lshl_add_u64 v[70:71], v[128:129], 0, s[12:13]
	global_load_dwordx4 v[120:123], v[68:69], off
	global_load_dwordx4 v[116:119], v[70:71], off
	s_add_i32 s100, s21, 1
	s_cmp_lt_i32 s100, s16
	s_cbranch_scc1 .LBB0_334_h1
	s_cmp_gt_i32 s21, s8
	s_cbranch_scc1 .LBB0_334_h1
	v_mov_b32_e32 v84, 0
	v_mov_b32_e32 v86, 0
	v_mov_b32_e32 v138, 0
	v_mov_b32_e32 v142, 0
	v_mov_b32_e32 v134, 0
	s_bitcmp1_b32 s21, 0
	v_mov_b32_e32 v140, 0
	s_cselect_b32 s12, 0x2400, 0
	v_mov_b32_e32 v132, 0
	v_add_u32_e32 v1, s12, v150
	v_mov_b32_e32 v136, 0
	s_waitcnt lgkmcnt(1)
	s_nop 0
	ds_read_b128 v[56:59], v1 offset:18464
	v_mov_b32_e32 v98, 0
	v_mov_b32_e32 v96, 0
	v_mov_b32_e32 v146, 0
	v_add_f32_e64 v35, -v152, v64
	v_exp_f32_e32 v90, v35
	v_add_f32_e64 v35, -v152, v65
	v_exp_f32_e32 v94, v35
	v_add_f32_e64 v35, -v152, v66
	v_exp_f32_e32 v88, v35
	v_add_f32_e64 v35, -v152, v67
	v_exp_f32_e32 v92, v35
	v_mov_b32_e32 v144, 0
	v_cvt_pk_bf16_f32 v62, v90, v94
	v_cvt_pk_bf16_f32 v63, v88, v92
	v_cvt_pk_bf16_f32 v61, v146, v144
	s_waitcnt lgkmcnt(1)
	ds_read_b128 v[52:55], v1 offset:23072
	v_cvt_pk_bf16_f32 v60, v98, v96
	v_add_u32_e32 v35, s22, v149
	s_waitcnt lgkmcnt(1)
	v_mfma_f32_32x32x16_bf16 v[2:17], v[56:59], v[60:63], v[2:17]
	ds_read_b128 v[72:75], v1 offset:18496
	v_add_f32_e64 v36, -v152, v36
	v_exp_f32_e32 v85, v36
	v_add_f32_e64 v36, -v152, v43
	v_exp_f32_e32 v137, v36
	v_add_f32_e64 v37, -v152, v37
	v_exp_f32_e32 v87, v37
	v_add_f32_e64 v37, -v152, v42
	v_exp_f32_e32 v133, v37
	v_add_f32_e64 v38, -v152, v38
	v_exp_f32_e32 v139, v38
	v_add_f32_e64 v38, -v152, v41
	v_exp_f32_e32 v141, v38
	v_add_f32_e64 v39, -v152, v39
	v_exp_f32_e32 v143, v39
	v_add_f32_e64 v39, -v152, v40
	v_exp_f32_e32 v135, v39
	v_cvt_pk_bf16_f32 v83, v133, v137
	ds_read_b128 v[36:39], v35 offset:4608
	ds_read_b128 v[56:59], v35 offset:4640
	v_cvt_pk_bf16_f32 v82, v135, v141
	s_waitcnt lgkmcnt(3)
	v_mfma_f32_32x32x16_bf16 v[18:33], v[52:55], v[60:63], v[18:33]
	ds_read_b128 v[52:55], v35
	ds_read_b128 v[60:63], v35 offset:4672
	ds_read_b128 v[64:67], v35 offset:4704
	ds_read_b128 v[68:71], v1 offset:23104
	ds_read_b128 v[154:157], v35 offset:32
	ds_read_b128 v[158:161], v35 offset:64
	ds_read_b128 v[162:165], v35 offset:96
	v_cvt_pk_bf16_f32 v80, v85, v87
	v_cvt_pk_bf16_f32 v81, v139, v143
	v_add_f32_e64 v35, -v152, v51
	v_exp_f32_e32 v93, v35
	v_add_f32_e64 v35, -v152, v44
	v_exp_f32_e32 v99, v35
	v_add_f32_e64 v35, -v152, v46
	v_exp_f32_e32 v147, v35
	v_add_f32_e64 v35, -v152, v50
	v_exp_f32_e32 v89, v35
	v_add_f32_e64 v40, -v152, v45
	v_add_f32_e64 v76, -v152, v47
	v_add_f32_e64 v78, -v152, v48
	v_exp_f32_e32 v97, v40
	v_add_f32_e64 v79, -v152, v49
	s_waitcnt lgkmcnt(8)
	v_mfma_f32_32x32x16_bf16 v[36:51], v[36:39], v[100:103], v[176:191]
	s_waitcnt lgkmcnt(7)
	v_mfma_f32_32x32x16_bf16 v[36:51], v[56:59], v[104:107], v[36:51]
	s_waitcnt lgkmcnt(5)
	v_mfma_f32_32x32x16_bf16 v[36:51], v[60:63], v[108:111], v[36:51]
	s_waitcnt lgkmcnt(4)
	v_mfma_f32_32x32x16_bf16 v[36:51], v[64:67], v[112:115], v[36:51]
	v_mfma_f32_32x32x16_bf16 v[52:67], v[52:55], v[100:103], v[202:217]
	s_waitcnt lgkmcnt(2)
	v_mfma_f32_32x32x16_bf16 v[52:67], v[154:157], v[104:107], v[52:67]
	s_waitcnt lgkmcnt(1)
	v_mfma_f32_32x32x16_bf16 v[52:67], v[158:161], v[108:111], v[52:67]
	v_exp_f32_e32 v145, v76
	v_cvt_pk_bf16_f32 v76, v99, v97
	v_cvt_pk_bf16_f32 v77, v147, v145
	v_exp_f32_e32 v91, v78
	v_exp_f32_e32 v95, v79
	s_waitcnt lgkmcnt(0)
	v_mfma_f32_32x32x16_bf16 v[52:67], v[162:165], v[112:115], v[52:67]
	v_cvt_pk_bf16_f32 v79, v89, v93
	v_cvt_pk_bf16_f32 v78, v91, v95
	ds_read_b128 v[154:157], v1 offset:18528
	ds_read_b128 v[158:161], v1 offset:23136
	v_mfma_f32_32x32x16_bf16 v[2:17], v[72:75], v[80:83], v[2:17]
	v_add_f32_e64 v72, v138, v142
	v_add_f32_e64 v73, v139, v143
	v_add_f32_e64 v74, v134, v140
	v_add_f32_e64 v75, v135, v141
	v_add_f32_e64 v132, v132, v136
	v_add_f32_e64 v133, v133, v137
	v_pk_add_f32 v[84:85], v[84:85], v[86:87]
	v_pk_add_f32 v[74:75], v[74:75], v[132:133]
	s_andn2_b64 vcc, exec, s[10:11]
	v_mfma_f32_32x32x16_bf16 v[18:33], v[68:71], v[80:83], v[18:33]
	v_add_f32_e64 v68, v84, v72
	v_add_f32_e64 v69, v85, v73
	v_add_f32_e64 v72, v90, v94
	v_add_f32_e64 v73, v91, v95
	v_add_f32_e64 v68, v68, v74
	v_add_f32_e64 v69, v69, v75
	v_pk_add_f32 v[74:75], v[88:89], v[92:93]
	v_pk_add_f32 v[70:71], v[146:147], v[144:145]
	v_pk_add_f32 v[72:73], v[72:73], v[74:75]
	v_pk_add_f32 v[74:75], v[98:99], v[96:97]
	s_waitcnt lgkmcnt(1)
	v_mfma_f32_32x32x16_bf16 v[2:17], v[154:157], v[76:79], v[2:17]
	v_add_f32_e64 v70, v74, v70
	v_add_f32_e64 v71, v75, v71
	v_add_f32_e64 v70, v70, v72
	v_add_f32_e64 v71, v71, v73
	v_add_f32_e64 v68, v68, v70
	v_add_f32_e64 v69, v69, v71
	v_add_f32_e32 v1, v68, v69
	s_waitcnt lgkmcnt(0)
	v_mfma_f32_32x32x16_bf16 v[18:33], v[158:161], v[76:79], v[18:33]
	v_add_f32_e32 v0, v0, v1
	s_cbranch_vccnz .LBB0_334_h1
	s_cmp_lt_i32 s20, s16
	s_cselect_b64 s[10:11], -1, 0
	s_cmp_ge_i32 s21, s8
	s_cselect_b64 s[12:13], -1, 0
	s_or_b64 s[10:11], s[12:13], s[10:11]
	s_and_b64 vcc, exec, s[10:11]
	s_cbranch_vccnz .LBB0_331_h1
	s_add_i32 s10, s19, s21
	s_max_i32 s10, s10, -7
	s_add_i32 s10, s10, 7
	s_min_u32 s10, s10, 14
	s_mulk_i32 s10, 0x1fc
	v_add_u32_e32 v1, s10, v151
	v_mov_b32_e32 v35, 0xf149f2ca
	ds_read_b32 v69, v1 offset:36992
	ds_read_b32 v71, v1 offset:36996
	ds_read_b32 v73, v1 offset:37000
	ds_read_b32 v75, v1 offset:37004
	ds_read_b32 v77, v1 offset:37024
	ds_read_b32 v79, v1 offset:37028
	ds_read_b32 v81, v1 offset:37032
	ds_read_b32 v83, v1 offset:37036
	ds_read_b32 v85, v1 offset:37056
	ds_read_b32 v87, v1 offset:37060
	ds_read_b32 v89, v1 offset:37064
	ds_read_b32 v91, v1 offset:37068
	ds_read_b32 v92, v1 offset:36960
	ds_read_b32 v93, v1 offset:37088
	ds_read_b32 v94, v1 offset:36964
	s_waitcnt lgkmcnt(14)
	v_add_f32_e32 v36, v36, v69
	ds_read_b32 v95, v1 offset:37092
	s_waitcnt lgkmcnt(14)
	v_add_f32_e32 v37, v37, v71
	ds_read_b32 v96, v1 offset:36968
	s_waitcnt lgkmcnt(14)
	v_add_f32_e32 v38, v38, v73
	ds_read_b32 v97, v1 offset:37096
	s_waitcnt lgkmcnt(14)
	v_add_f32_e32 v39, v39, v75
	ds_read_b32 v98, v1 offset:36972
	s_waitcnt lgkmcnt(14)
	v_add_f32_e32 v40, v40, v77
	ds_read_b32 v99, v1 offset:37100
	s_waitcnt lgkmcnt(14)
	v_add_f32_e32 v41, v41, v79
	s_waitcnt lgkmcnt(13)
	v_add_f32_e32 v42, v42, v81
	s_waitcnt lgkmcnt(12)
	v_add_f32_e32 v43, v43, v83
	s_waitcnt lgkmcnt(11)
	v_add_f32_e32 v44, v44, v85
	s_waitcnt lgkmcnt(10)
	v_add_f32_e32 v45, v45, v87
	s_waitcnt lgkmcnt(9)
	v_add_f32_e32 v46, v46, v89
	s_waitcnt lgkmcnt(8)
	v_add_f32_e32 v47, v47, v91
	s_waitcnt lgkmcnt(7)
	v_add_f32_e32 v64, v64, v92
	s_waitcnt lgkmcnt(6)
	v_add_f32_e32 v48, v48, v93
	s_waitcnt lgkmcnt(5)
	v_add_f32_e32 v65, v65, v94
	s_waitcnt lgkmcnt(4)
	v_add_f32_e32 v49, v49, v95
	s_waitcnt lgkmcnt(3)
	v_add_f32_e32 v66, v66, v96
	s_waitcnt lgkmcnt(2)
	v_add_f32_e32 v50, v50, v97
	s_waitcnt lgkmcnt(1)
	v_add_f32_e32 v67, v67, v98
	s_waitcnt lgkmcnt(0)
	v_add_f32_e32 v51, v51, v99
	s_branch .LBB0_332_h1
